# v19 + pass-0 first K/V tile loads issued at the end of the item set-up (before the gate ladder)
# baseline (speedup 1.0000x reference)
; template <int PM> DI void attn_phase(const Params& p, int l, char* smem, int* s_item, int wv, int cidx) {
;     ...
;     int qoff, koff, voff;
;     if (mixer == 0) { qoff = head * 128; koff = 512 + head * 128; voff = 1024 + head * 128; }
;     else if (mixer == 1) { qoff = 1536 + head * 128; koff = 2048 + (head >> 1) * 128; voff = 2304 + (head >> 1) * 128; }
;     else if (mixer == 2) { qoff = 2560 + head * 128; koff = 3072 + head * 128; voff = 3584 + head * 128; }
;     else { qoff = 4096 + head * 128; koff = 4608 + (head >> 1) * 128; voff = 4864 + (head >> 1) * 128; }
;     const int Rb = b * TPB;
;     const int Rq = Rb + (isctx ? 0 : 256) + qt * 256 + w * 32 + l31;
;     int nplain, nlocal = 0, local_t0 = 0, mode = 0;
;     if (isctx) nplain = 4;
;     else if (mixer == 0 || mixer == 3) nplain = 36;
;     else if (mixer == 1) {
;       nplain = 4; mode = 1;
;       const int ts = max(0, qt * 256 - 128), te = min(2048, qt * 256 + 384);
;       local_t0 = ts; nlocal = (te - ts) >> 6;
;     } else {
;       nplain = 4; mode = 2;
;       const int r0 = 4 * qt;
;       const int lo = min(max(r0 - 4, 0), 24), hi = min(max(r0 - 1, 0), 24) + 8;
;       local_t0 = lo * 64; nlocal = hi - lo;
;     }
;     const int ntl = nplain + nlocal;
;     const int tq0 = qt * 256 + w * 32;
;     const int tq = tq0 + l31;
;     const int qrow = tq0 >> 6, qcol = tq & 63;
;     const int kr0 = min(max(qrow - 4, 0), 24);
;     const int cstart = min(max(qcol - 8, 0), 48);
;     if (mode == 2) {
;       if (tid < 465) rpb_s[tid] = p.rpb[(l * 4 + head) * 465 + tid] * LOG2E;
;     }
;     {
;       const u16* gsrc = p.P + (size_t)(Rb + (isctx ? 0 : 256) + qt * 256 + (tid >> 4)) * INW + 5120 + mixer * 512 + head * 128 + (tid & 15) * 8;
;       u32x4 gt[8];
; #pragma unroll
;       for (int j = 0; j < 8; ++j) gt[j] = *(const u32x4*)(gsrc + (size_t)j * 32 * INW);
; #pragma unroll
;       for (int j = 0; j < 8; ++j) *(u32x4*)(gate_s + ((tid >> 4) + 32 * j) * 264 + (tid & 15) * 16) = gt[j];
;     }
.LBB0_406:
	s_or_b64 exec, exec, s[2:3]
	v_readlane_b32 s2, v254, 57
	s_add_i32 s88, s18, s2
	s_ashr_i32 s82, s88, 6
	s_max_i32 s2, s82, 4
	s_add_i32 s2, s2, -4
	s_xor_b64 s[78:79], s[14:15], -1
	s_add_i32 s81, s80, s11
	s_min_u32 s83, s2, 24
	s_and_b32 s84, s7, 3
	s_and_b64 s[0:1], exec, s[0:1]
	s_cselect_b32 s0, 0, 0x100
	s_mulk_i32 s84, 0x900
	s_add_i32 s0, s18, s0
	v_readlane_b32 s36, v253, 21
	s_add_i32 s2, s0, s84
	v_readlane_b32 s50, v253, 35
	v_readlane_b32 s51, v253, 36
	v_add_u32_e32 v0, s2, v239
	s_movk_i32 s22, 0x3800
	v_mov_b64_e32 v[14:15], s[50:51]
	v_mad_i64_i32 v[2:3], s[0:1], v0, s22, v[14:15]
	s_mov_b32 s17, s21
	s_lshl_b32 s16, s86, 10
	v_lshl_add_u64 v[2:3], v[2:3], 0, s[16:17]
	s_lshl_b32 s0, s20, 1
	s_mov_b32 s1, s21
	v_lshl_add_u64 v[2:3], v[2:3], 0, s[0:1]
	v_mov_b32_e32 v205, v1
	v_lshl_add_u64 v[60:61], v[2:3], 0, v[204:205]
	s_movk_i32 s3, 0x2000
	v_add_co_u32_e32 v2, vcc, s3, v60
	s_mov_b32 s3, 0x72000
	s_nop 0
	v_addc_co_u32_e32 v3, vcc, 0, v61, vcc
	v_add_co_u32_e32 v6, vcc, s3, v60
	s_mov_b32 s3, 0xe2000
	s_nop 0
	v_addc_co_u32_e32 v7, vcc, 0, v61, vcc
	v_add_co_u32_e32 v10, vcc, s3, v60
	s_mov_b32 s3, 0x152000
	s_nop 0
	v_addc_co_u32_e32 v11, vcc, 0, v61, vcc
	v_add_co_u32_e32 v48, vcc, s3, v60
	s_mov_b32 s3, 0x1c2000
	s_nop 0
	v_addc_co_u32_e32 v49, vcc, 0, v61, vcc
	v_add_co_u32_e32 v52, vcc, s3, v60
	s_mov_b32 s3, 0x232000
	s_nop 0
	v_addc_co_u32_e32 v53, vcc, 0, v61, vcc
	v_add_co_u32_e32 v56, vcc, s3, v60
	s_mov_b32 s3, 0x2a2000
	s_nop 0
	v_addc_co_u32_e32 v57, vcc, 0, v61, vcc
	v_add_co_u32_e32 v62, vcc, s3, v60
	s_mov_b32 s3, 0x312000
	s_nop 0
	v_addc_co_u32_e32 v63, vcc, 0, v61, vcc
	v_add_co_u32_e32 v64, vcc, s3, v60
	global_load_dwordx4 v[16:19], v[2:3], off offset:2048
	s_nop 0
	global_load_dwordx4 v[20:23], v[6:7], off offset:2048
	v_addc_co_u32_e32 v65, vcc, 0, v61, vcc
	global_load_dwordx4 v[24:27], v[10:11], off offset:2048
	s_nop 0
	global_load_dwordx4 v[28:31], v[48:49], off offset:2048
	s_nop 0
	global_load_dwordx4 v[32:35], v[52:53], off offset:2048
	s_nop 0
	global_load_dwordx4 v[36:39], v[56:57], off offset:2048
	s_nop 0
	global_load_dwordx4 v[40:43], v[62:63], off offset:2048
	s_nop 0
	global_load_dwordx4 v[44:47], v[64:65], off offset:2048
	v_readlane_b32 s14, v254, 61
	v_readlane_b32 s15, v254, 62
	s_and_b64 s[14:15], s[14:15], exec
	v_add_u32_e32 v68, s2, v241
	s_cselect_b32 s13, 2, 1
	s_lshl_b32 s2, s20, 2
	v_ashrrev_i32_e32 v69, 31, v68
	s_cmp_gt_i32 s81, 1
	v_lshlrev_b64 v[70:71], 11, v[68:69]
	s_cselect_b64 s[14:15], -1, 0
	s_mov_b32 s3, s21
	v_lshl_add_u64 v[70:71], s[92:93], 0, v[70:71]
	v_writelane_b32 v255, s14, 1
	s_cmp_gt_i32 s81, 0
	v_lshl_add_u64 v[70:71], v[70:71], 0, s[2:3]
	v_writelane_b32 v255, s15, 2
	s_cselect_b64 s[2:3], -1, 0
	v_writelane_b32 v255, s2, 3
	v_bitop3_b32 v205, s88, 63, v240 bitop3:0xc8
	v_sub_u32_e64 v0, v205, 8 clamp
	v_writelane_b32 v255, s3, 4
	s_add_i32 s2, s13, -1
	v_writelane_b32 v255, s13, 5
	s_cmp_eq_u32 s86, 1
	v_min_u32_e32 v0, 48, v0
	v_writelane_b32 v255, s2, 6
	s_cselect_b64 s[2:3], -1, 0
	s_mov_b32 s7, s21
	v_writelane_b32 v255, s2, 7
	s_mov_b32 s9, s21
	s_lshl_b64 s[96:97], s[6:7], 1
	v_writelane_b32 v255, s3, 8
	v_readlane_b32 s37, v253, 22
	v_readlane_b32 s38, v253, 23
	v_readlane_b32 s39, v253, 24
	v_readlane_b32 s40, v253, 25
	v_readlane_b32 s41, v253, 26
	v_sub_u32_e32 v6, v198, v0
	v_mad_i64_i32 v[4:5], s[2:3], v68, s22, v[14:15]
	v_cmp_gt_u32_e64 s[6:7], 16, v6
	v_sub_u32_e32 v6, v248, v0
	v_lshl_add_u64 v[4:5], s[8:9], 1, v[4:5]
	v_cmp_gt_u32_e64 s[8:9], 16, v6
	v_add_u32_e32 v6, 8, v198
	v_sub_u32_e32 v10, v6, v0
	v_add_u32_e32 v6, 9, v198
	v_sub_u32_e32 v11, v6, v0
	v_add_u32_e32 v6, 10, v198
	v_sub_u32_e32 v12, v6, v0
	v_add_u32_e32 v6, 11, v198
	v_sub_u32_e32 v13, v6, v0
	v_add_u32_e32 v6, 16, v198
	v_sub_u32_e32 v14, v6, v0
	v_add_u32_e32 v6, 17, v198
	v_sub_u32_e32 v15, v6, v0
	v_add_u32_e32 v6, 18, v198
	v_sub_u32_e32 v48, v6, v0
	v_add_u32_e32 v6, 19, v198
	v_sub_u32_e32 v49, v6, v0
	v_add_u32_e32 v6, 24, v198
	v_sub_u32_e32 v50, v6, v0
	v_add_u32_e32 v6, 25, v198
	v_sub_u32_e32 v51, v6, v0
	v_add_u32_e32 v6, 26, v198
	v_sub_u32_e32 v52, v6, v0
	v_add_u32_e32 v6, 27, v198
	v_sub_u32_e32 v53, v6, v0
	v_add_u32_e32 v6, 32, v198
	v_sub_u32_e32 v54, v6, v0
	v_add_u32_e32 v6, 33, v198
	v_sub_u32_e32 v55, v6, v0
	v_add_u32_e32 v6, 34, v198
	v_sub_u32_e32 v56, v6, v0
	v_add_u32_e32 v6, 35, v198
	v_readlane_b32 s42, v253, 27
	v_readlane_b32 s43, v253, 28
	v_readlane_b32 s44, v253, 29
	v_readlane_b32 s45, v253, 30
	v_readlane_b32 s46, v253, 31
	v_readlane_b32 s47, v253, 32
	v_readlane_b32 s48, v253, 33
; template <int PM> DI void attn_phase(const Params& p, int l, char* smem, int* s_item, int wv, int cidx) {
;     ...
;     {
;       const u16* gsrc = p.P + (size_t)(Rb + (isctx ? 0 : 256) + qt * 256 + (tid >> 4)) * INW + 5120 + mixer * 512 + head * 128 + (tid & 15) * 8;
;       u32x4 gt[8];
; #pragma unroll
;       for (int j = 0; j < 8; ++j) gt[j] = *(const u32x4*)(gsrc + (size_t)j * 32 * INW);
; #pragma unroll
;       for (int j = 0; j < 8; ++j) *(u32x4*)(gate_s + ((tid >> 4) + 32 * j) * 264 + (tid & 15) * 16) = gt[j];
;     }
;     const int npass = (mixer == 0) ? 2 : 1;
;     const bool full_d = (mixer != 0);
;     float* asave = p.asave + (size_t)Rq * 512 + head * 128 + 4 * h;
;     for (int pass = 0; pass < npass; ++pass) {
;       bf16x8 qf[8];
;       {
;         const u16* qp = p.P + (size_t)Rq * INW + qoff + pass * 64 + h * 8;
; #pragma unroll
;         for (int ks = 0; ks < 4; ++ks) qf[ks] = *(const bf16x8*)(qp + ks * 16);
; #pragma unroll
;         for (int ks = 4; ks < 8; ++ks) qf[ks] = full_d ? *(const bf16x8*)(qp + ks * 16) : (bf16x8){0, 0, 0, 0, 0, 0, 0, 0};
;       }
;       const int dofs_b = pass * 128;
;       f32x16 Oacc[4];
; #pragma unroll
;       for (int db = 0; db < 4; ++db)
; #pragma unroll
;         for (int e = 0; e < 16; ++e) Oacc[db][e] = 0.f;
;       float m = -1e30f, lsum = 0.f;
;       u32x4 kst[2], vst[2];
;       __syncthreads();
;       {
;         const u16* base = p.P + (size_t)(Rb + trow) * INW + tch * 8;
; #pragma unroll
;         for (int j = 0; j < 2; ++j) {
;           kst[j] = *(const u32x4*)(base + (size_t)j * 32 * INW + koff);
;           vst[j] = *(const u32x4*)(base + (size_t)j * 32 * INW + voff);
;         }
	v_readlane_b32 s49, v253, 34
	v_sub_u32_e32 v57, v6, v0
	v_add_u32_e32 v6, 40, v198
	s_mov_b32 s11, s21
	s_ashr_i32 s13, s12, 31
	v_readlane_b32 s36, v253, 5
	v_sub_u32_e32 v58, v6, v0
	v_add_u32_e32 v6, 41, v198
	s_add_i32 s87, s88, 0xffffff80
	s_addk_i32 s88, 0x9f
	s_lshl_b64 s[76:77], s[10:11], 1
	s_lshl_b64 s[2:3], s[12:13], 2
	v_readlane_b32 s46, v253, 15
	v_sub_u32_e32 v59, v6, v0
	v_add_u32_e32 v6, 42, v198
	v_readlane_b32 s47, v253, 16
	s_add_u32 s2, s46, s2
	v_sub_u32_e32 v60, v6, v0
	v_add_u32_e32 v6, 43, v198
	s_addc_u32 s3, s47, s3
	v_sub_u32_e32 v61, v6, v0
	v_add_u32_e32 v6, 48, v198
	v_lshlrev_b64 v[2:3], 12, v[68:69]
	v_writelane_b32 v255, s2, 9
	v_sub_u32_e32 v62, v6, v0
	v_add_u32_e32 v6, 49, v198
	v_writelane_b32 v255, s3, 10
	v_lshl_add_u64 v[2:3], s[56:57], 0, v[2:3]
	s_mov_b32 s3, s21
	v_sub_u32_e32 v63, v6, v0
	v_add_u32_e32 v6, 50, v198
	v_add_u32_e32 v72, s84, v239
	v_writelane_b32 v254, s2, 59
	v_lshl_add_u64 v[2:3], v[2:3], 0, s[16:17]
	v_sub_u32_e32 v64, v6, v0
	v_add_u32_e32 v6, 51, v198
	v_writelane_b32 v254, s3, 60
	v_lshl_add_u64 v[2:3], v[2:3], 0, s[0:1]
	v_sub_u32_e32 v65, v6, v0
	v_add_u32_e32 v6, 56, v198
	v_lshl_add_u64 v[208:209], v[200:201], 1, v[4:5]
	v_mad_i64_i32 v[4:5], s[0:1], v72, s22, v[202:203]
	s_mov_b64 s[2:3], 0x70000
	v_add_u32_e32 v73, 64, v72
	v_sub_u32_e32 v66, v6, v0
	v_add_u32_e32 v6, 57, v198
	v_lshl_add_u64 v[210:211], v[4:5], 0, s[96:97]
	v_lshl_add_u64 v[212:213], v[4:5], 0, s[76:77]
	v_lshl_add_u64 v[4:5], v[4:5], 0, s[2:3]
	v_sub_u32_e32 v67, v6, v0
	v_add_u32_e32 v6, 58, v198
	v_lshl_add_u64 v[214:215], v[4:5], 0, s[96:97]
	v_lshl_add_u64 v[216:217], v[4:5], 0, s[76:77]
	v_mad_i64_i32 v[4:5], s[0:1], v73, s22, v[202:203]
	v_sub_u32_e32 v68, v6, v0
	v_add_u32_e32 v6, 59, v198
	s_lshl_b32 s0, s80, 6
	v_readlane_b32 s37, v253, 6
	v_readlane_b32 s38, v253, 7
	v_readlane_b32 s39, v253, 8
	v_readlane_b32 s40, v253, 9
	v_readlane_b32 s41, v253, 10
	v_readlane_b32 s42, v253, 11
	v_readlane_b32 s43, v253, 12
	v_readlane_b32 s44, v253, 13
	v_readlane_b32 s45, v253, 14
	v_readlane_b32 s48, v253, 17
	v_readlane_b32 s49, v253, 18
	v_readlane_b32 s50, v253, 19
	v_readlane_b32 s51, v253, 20
	v_sub_u32_e32 v8, v249, v0
	v_sub_u32_e32 v9, v250, v0
	v_sub_u32_e32 v0, v6, v0
	v_lshl_add_u64 v[6:7], v[4:5], 0, s[2:3]
	s_sub_i32 s0, s19, s0
	v_lshl_add_u64 v[206:207], v[198:199], 2, v[70:71]
	s_movk_i32 s85, 0x3800
	s_mov_b64 s[98:99], 0x70000
	v_lshl_add_u64 v[218:219], v[6:7], 0, s[76:77]
	v_lshl_add_u64 v[220:221], v[6:7], 0, s[96:97]
	v_lshl_add_u64 v[222:223], v[4:5], 0, s[76:77]
	v_lshl_add_u64 v[224:225], v[4:5], 0, s[96:97]
	v_lshl_add_u64 v[226:227], v[198:199], 1, v[2:3]
	v_writelane_b32 v255, s0, 11
	v_subrev_u32_e32 v228, s18, v197
	s_add_i32 s90, s84, 0x180
	v_mov_b32_e32 v229, 0
	s_mov_b32 s91, 0
	v_cmp_gt_u32_e64 s[10:11], 16, v8
	v_cmp_gt_u32_e64 s[12:13], 16, v9
	v_cmp_gt_u32_e64 s[14:15], 16, v10
	v_cmp_gt_u32_e64 s[16:17], 16, v11
	v_cmp_gt_u32_e64 s[18:19], 16, v12
	v_cmp_gt_u32_e64 s[20:21], 16, v13
	v_cmp_gt_u32_e64 s[22:23], 16, v14
	v_cmp_gt_u32_e64 s[24:25], 16, v15
	v_cmp_gt_u32_e64 s[26:27], 16, v48
	v_cmp_gt_u32_e64 s[28:29], 16, v49
	v_cmp_gt_u32_e64 s[30:31], 16, v50
	v_cmp_gt_u32_e64 s[34:35], 16, v51
	v_cmp_gt_u32_e64 s[36:37], 16, v52
	v_cmp_gt_u32_e64 s[38:39], 16, v53
	v_cmp_gt_u32_e64 s[40:41], 16, v54
	v_cmp_gt_u32_e64 s[42:43], 16, v55
	v_cmp_gt_u32_e64 s[44:45], 16, v56
	v_cmp_gt_u32_e64 s[46:47], 16, v57
	v_cmp_gt_u32_e64 s[48:49], 16, v58
	v_cmp_gt_u32_e64 s[50:51], 16, v59
	v_cmp_gt_u32_e64 s[52:53], 16, v60
	v_cmp_gt_u32_e64 s[54:55], 16, v61
	v_cmp_gt_u32_e64 s[56:57], 16, v62
	v_cmp_gt_u32_e64 s[58:59], 16, v63
	v_cmp_gt_u32_e64 s[60:61], 16, v64
	v_cmp_gt_u32_e64 s[62:63], 16, v65
	v_cmp_gt_u32_e64 s[64:65], 16, v66
	v_cmp_gt_u32_e64 s[66:67], 16, v67
	v_cmp_gt_u32_e64 s[68:69], 16, v68
	v_cmp_gt_u32_e64 s[70:71], 16, v0
	global_load_dwordx4 v[180:183], v[210:211], off
	global_load_dwordx4 v[184:187], v[212:213], off
	global_load_dwordx4 v[188:191], v[214:215], off
	global_load_dwordx4 v[192:195], v[216:217], off
	s_waitcnt vmcnt(11)
	ds_write_b128 v251, v[16:19]
	s_waitcnt vmcnt(10)
	ds_write_b128 v251, v[20:23] offset:8448
	s_waitcnt vmcnt(9)
	ds_write_b128 v251, v[24:27] offset:16896
	s_waitcnt vmcnt(8)
	ds_write_b128 v251, v[28:31] offset:25344
	s_waitcnt vmcnt(7)
	ds_write_b128 v251, v[32:35] offset:33792
	s_waitcnt vmcnt(6)
	ds_write_b128 v251, v[36:39] offset:42240
	s_waitcnt vmcnt(5)
	ds_write_b128 v251, v[40:43] offset:50688
	s_waitcnt vmcnt(4)
	ds_write_b128 v251, v[44:47] offset:59136
	s_branch .LBB0_409

; template <int PM> DI void attn_phase(const Params& p, int l, char* smem, int* s_item, int wv, int cidx) {
;     ...
;       __syncthreads();
;       {
;         const u16* base = p.P + (size_t)(Rb + trow) * INW + tch * 8;
; #pragma unroll
;         for (int j = 0; j < 2; ++j) {
;           kst[j] = *(const u32x4*)(base + (size_t)j * 32 * INW + koff);
;           vst[j] = *(const u32x4*)(base + (size_t)j * 32 * INW + voff);
;         }
; #pragma unroll
;         for (int j = 0; j < 2; ++j) {
;           *(u32x4*)(Kb0 + (trow + 32 * j) * 272 + tch * 16) = kst[j];
;           *(u32x4*)(Vb0 + (trow + 32 * j) * 320 + tch * 16) = vst[j];
;         }
;         const int R1 = (1 < nplain) ? Rb + 64 : Rb + 256 + local_t0 + 64 * (1 - nplain);
;         const u16* b1 = p.P + (size_t)(R1 + trow) * INW + tch * 8;
;         if (ntl > 1) {
; #pragma unroll
;           for (int j = 0; j < 2; ++j) {
;             kst[j] = *(const u32x4*)(b1 + (size_t)j * 32 * INW + koff);
;             vst[j] = *(const u32x4*)(b1 + (size_t)j * 32 * INW + voff);
;           }
;         }
.LBB0_418:
	s_waitcnt lgkmcnt(0)
	s_barrier
	s_cmp_eq_u32 s91, 0
	s_cbranch_scc1 .Lt0_done
	global_load_dwordx4 v[180:183], v[210:211], off
	global_load_dwordx4 v[184:187], v[212:213], off
	global_load_dwordx4 v[188:191], v[214:215], off
	global_load_dwordx4 v[192:195], v[216:217], off
.Lt0_done:
	v_readlane_b32 s0, v255, 1
	v_readlane_b32 s1, v255, 2
	v_add_u32_e32 v0, v196, v246
	v_add_u32_e32 v2, v196, v247
	s_andn2_b64 vcc, exec, s[0:1]
	s_waitcnt vmcnt(3)
	ds_write_b128 v0, v[180:183]
	s_waitcnt vmcnt(2)
	ds_write_b128 v2, v[184:187] offset:34816
	s_waitcnt vmcnt(1)
	ds_write_b128 v0, v[188:191] offset:8704
	s_waitcnt vmcnt(0)
	ds_write_b128 v2, v[192:195] offset:45056
	s_cbranch_vccnz .LBB0_420
	global_load_dwordx4 v[180:183], v[224:225], off
	global_load_dwordx4 v[184:187], v[222:223], off
	global_load_dwordx4 v[188:191], v[220:221], off
	global_load_dwordx4 v[192:195], v[218:219], off
